# P5/P12: the 16 per-row scale lane-permutes (ds_bpermute) issued as one batch at the top of each 16-row group instead of one LDS round trip per row
# speedup vs baseline: 1.0081x; 1.0081x over previous
.LBB0_214:
	s_cmp_lt_u32 s39, 64
	s_cselect_b64 vcc, -1, 0
	v_and_or_b32 v15, s39, 48, v94
	v_cndmask_b32_e32 v14, v11, v10, vcc
	v_lshlrev_b32_e32 v15, 2, v15
	ds_bpermute_b32 v150, v15, v14
	ds_bpermute_b32 v152, v15, v14 offset:4
	ds_bpermute_b32 v154, v15, v14 offset:8
	ds_bpermute_b32 v156, v15, v14 offset:12
	ds_bpermute_b32 v158, v15, v14 offset:16
	ds_bpermute_b32 v160, v15, v14 offset:20
	ds_bpermute_b32 v162, v15, v14 offset:24
	ds_bpermute_b32 v164, v15, v14 offset:28
	ds_bpermute_b32 v166, v15, v14 offset:32
	ds_bpermute_b32 v168, v15, v14 offset:36
	ds_bpermute_b32 v170, v15, v14 offset:40
	ds_bpermute_b32 v172, v15, v14 offset:44
	ds_bpermute_b32 v174, v15, v14 offset:48
	ds_bpermute_b32 v176, v15, v14 offset:52
	ds_bpermute_b32 v178, v15, v14 offset:56
	ds_bpermute_b32 v180, v15, v14 offset:60
	s_waitcnt vmcnt(31)
	v_lshlrev_b32_e32 v48, 16, v45
	v_and_b32_e32 v49, 0xffff0000, v45
	s_waitcnt vmcnt(30)
	v_lshlrev_b32_e32 v50, 16, v44
	v_and_b32_e32 v51, 0xffff0000, v44
	s_waitcnt lgkmcnt(0)
	v_pk_mul_f32 v[48:49], v[150:151], v[48:49] op_sel_hi:[0,1]
	v_pk_mul_f32 v[44:45], v[150:151], v[50:51] op_sel_hi:[0,1]
	s_waitcnt vmcnt(1)
	v_pk_mul_f32 v[46:47], v[74:75], v[4:5]
	v_lshlrev_b32_e32 v50, 16, v42
	v_pk_fma_f32 v[8:9], v[70:71], v[8:9], v[46:47]
	s_waitcnt vmcnt(0)
	v_pk_mul_f32 v[46:47], v[76:77], v[2:3]
	v_pk_fma_f32 v[8:9], v[78:79], v[48:49], v[8:9]
	v_pk_fma_f32 v[6:7], v[72:73], v[6:7], v[46:47]
	v_mul_f32_e32 v46, 0xbfb8aa3b, v8
	v_exp_f32_e32 v46, v46
	v_pk_fma_f32 v[6:7], v[80:81], v[44:45], v[6:7]
	v_and_b32_e32 v47, 0xffff0000, v43
	v_and_b32_e32 v51, 0xffff0000, v42
	v_add_f32_e32 v46, 1.0, v46
	v_rcp_f32_e32 v46, v46
	s_add_i32 s40, s39, 14
	s_mov_b64 s[22:23], -1
	s_andn2_b64 vcc, exec, s[16:17]
	v_mul_f32_e32 v8, v8, v46
	v_mul_f32_e32 v6, v6, v8
	v_mul_f32_e32 v8, 0xbfb8aa3b, v9
	v_exp_f32_e32 v8, v8
	v_lshlrev_b32_e32 v46, 16, v43
	v_add_f32_e32 v8, 1.0, v8
	v_rcp_f32_e32 v8, v8
	s_nop 0
	v_mul_f32_e32 v8, v9, v8
	v_mul_f32_e32 v7, v7, v8
	v_cvt_pk_bf16_f32 v6, v6, v7
	s_waitcnt lgkmcnt(0)
	v_pk_mul_f32 v[46:47], v[152:153], v[46:47] op_sel_hi:[0,1]
	v_pk_mul_f32 v[42:43], v[152:153], v[50:51] op_sel_hi:[0,1]
	v_pk_mul_f32 v[8:9], v[74:75], v[48:49]
	s_nop 0
	v_pk_fma_f32 v[4:5], v[70:71], v[4:5], v[8:9]
	v_pk_mul_f32 v[8:9], v[76:77], v[44:45]
	v_pk_fma_f32 v[4:5], v[78:79], v[46:47], v[4:5]
	v_pk_fma_f32 v[2:3], v[72:73], v[2:3], v[8:9]
	v_mul_f32_e32 v7, 0xbfb8aa3b, v4
	v_exp_f32_e32 v7, v7
	v_pk_fma_f32 v[2:3], v[80:81], v[42:43], v[2:3]
	v_lshlrev_b32_e32 v8, 16, v40
	v_and_b32_e32 v9, 0xffff0000, v40
	v_add_f32_e32 v7, 1.0, v7
	v_rcp_f32_e32 v7, v7
	s_nop 0
	v_mul_f32_e32 v4, v4, v7
	v_mul_f32_e32 v2, v2, v4
	v_mul_f32_e32 v4, 0xbfb8aa3b, v5
	v_exp_f32_e32 v4, v4
	s_nop 0
	v_add_f32_e32 v4, 1.0, v4
	v_rcp_f32_e32 v4, v4
	s_nop 0
	v_mul_f32_e32 v4, v5, v4
	v_mul_f32_e32 v3, v3, v4
	v_cvt_pk_bf16_f32 v7, v2, v3
	v_lshlrev_b32_e32 v4, 16, v41
	v_and_b32_e32 v5, 0xffff0000, v41
	v_pk_mul_f32 v[40:41], v[76:77], v[42:43]
	s_waitcnt lgkmcnt(0)
	v_pk_mul_f32 v[4:5], v[154:155], v[4:5] op_sel_hi:[0,1]
	v_pk_mul_f32 v[2:3], v[154:155], v[8:9] op_sel_hi:[0,1]
	v_pk_mul_f32 v[8:9], v[74:75], v[46:47]
	v_pk_fma_f32 v[40:41], v[72:73], v[44:45], v[40:41]
	v_pk_fma_f32 v[8:9], v[70:71], v[48:49], v[8:9]
	v_pk_fma_f32 v[40:41], v[80:81], v[2:3], v[40:41]
	v_pk_fma_f32 v[8:9], v[78:79], v[4:5], v[8:9]
	v_and_b32_e32 v45, 0xffff0000, v39
	v_mul_f32_e32 v44, 0xbfb8aa3b, v8
	v_exp_f32_e32 v44, v44
	v_lshlrev_b32_e32 v48, 16, v38
	v_and_b32_e32 v49, 0xffff0000, v38
	v_add_f32_e32 v44, 1.0, v44
	v_rcp_f32_e32 v44, v44
	s_nop 0
	v_mul_f32_e32 v8, v8, v44
	v_mul_f32_e32 v8, v40, v8
	v_mul_f32_e32 v40, 0xbfb8aa3b, v9
	v_exp_f32_e32 v40, v40
	v_lshlrev_b32_e32 v44, 16, v39
	v_add_f32_e32 v40, 1.0, v40
	v_rcp_f32_e32 v40, v40
	s_nop 0
	v_mul_f32_e32 v9, v9, v40
	v_mul_f32_e32 v9, v41, v9
	v_cvt_pk_bf16_f32 v8, v8, v9
	s_waitcnt lgkmcnt(0)
	v_pk_mul_f32 v[44:45], v[156:157], v[44:45] op_sel_hi:[0,1]
	v_pk_mul_f32 v[38:39], v[156:157], v[48:49] op_sel_hi:[0,1]
	v_pk_mul_f32 v[40:41], v[74:75], v[4:5]
	s_nop 0
	v_pk_fma_f32 v[40:41], v[70:71], v[46:47], v[40:41]
	v_pk_mul_f32 v[46:47], v[76:77], v[2:3]
	v_pk_fma_f32 v[40:41], v[78:79], v[44:45], v[40:41]
	v_pk_fma_f32 v[42:43], v[72:73], v[42:43], v[46:47]
	v_mul_f32_e32 v9, 0xbfb8aa3b, v40
	v_exp_f32_e32 v9, v9
	v_pk_fma_f32 v[42:43], v[80:81], v[38:39], v[42:43]
	v_lshlrev_b32_e32 v46, 16, v20
	v_and_b32_e32 v47, 0xffff0000, v20
	v_add_f32_e32 v9, 1.0, v9
	v_rcp_f32_e32 v9, v9
	s_nop 0
	v_mul_f32_e32 v9, v40, v9
	v_mul_f32_e32 v40, 0xbfb8aa3b, v41
	v_exp_f32_e32 v40, v40
	v_mul_f32_e32 v9, v42, v9
	v_lshlrev_b32_e32 v42, 16, v37
	v_add_f32_e32 v40, 1.0, v40
	v_rcp_f32_e32 v40, v40
	s_nop 0
	v_mul_f32_e32 v40, v41, v40
	v_mul_f32_e32 v40, v43, v40
	v_cvt_pk_bf16_f32 v9, v9, v40
	v_and_b32_e32 v43, 0xffff0000, v37
	v_and_b32_e32 v37, 0xffff0000, v24
	s_waitcnt lgkmcnt(0)
	v_pk_mul_f32 v[42:43], v[158:159], v[42:43] op_sel_hi:[0,1]
	v_pk_mul_f32 v[40:41], v[158:159], v[46:47] op_sel_hi:[0,1]
	v_pk_mul_f32 v[46:47], v[74:75], v[44:45]
	s_nop 0
	v_pk_fma_f32 v[4:5], v[70:71], v[4:5], v[46:47]
	v_pk_mul_f32 v[46:47], v[76:77], v[38:39]
	v_pk_fma_f32 v[4:5], v[78:79], v[42:43], v[4:5]
	v_pk_fma_f32 v[2:3], v[72:73], v[2:3], v[46:47]
	v_mul_f32_e32 v20, 0xbfb8aa3b, v4
	v_exp_f32_e32 v20, v20
	v_pk_fma_f32 v[2:3], v[80:81], v[40:41], v[2:3]
	v_add_f32_e32 v20, 1.0, v20
	v_rcp_f32_e32 v20, v20
	s_nop 0
	v_mul_f32_e32 v4, v4, v20
	v_mul_f32_e32 v2, v2, v4
	v_mul_f32_e32 v4, 0xbfb8aa3b, v5
	v_exp_f32_e32 v4, v4
	s_nop 0
	v_add_f32_e32 v4, 1.0, v4
	v_rcp_f32_e32 v4, v4
	s_nop 0
	v_mul_f32_e32 v4, v5, v4
	v_mul_f32_e32 v3, v3, v4
	v_cvt_pk_bf16_f32 v20, v2, v3
	v_lshlrev_b32_e32 v4, 16, v36
	v_and_b32_e32 v5, 0xffff0000, v36
	v_lshlrev_b32_e32 v36, 16, v24
	s_waitcnt lgkmcnt(0)
	v_pk_mul_f32 v[4:5], v[160:161], v[4:5] op_sel_hi:[0,1]
	v_pk_mul_f32 v[2:3], v[160:161], v[36:37] op_sel_hi:[0,1]
	v_pk_mul_f32 v[36:37], v[74:75], v[42:43]
	s_nop 0
	v_pk_fma_f32 v[36:37], v[70:71], v[44:45], v[36:37]
	v_pk_mul_f32 v[44:45], v[76:77], v[40:41]
	v_pk_fma_f32 v[36:37], v[78:79], v[4:5], v[36:37]
	v_pk_fma_f32 v[38:39], v[72:73], v[38:39], v[44:45]
	v_mul_f32_e32 v24, 0xbfb8aa3b, v36
	v_exp_f32_e32 v24, v24
	v_pk_fma_f32 v[38:39], v[80:81], v[2:3], v[38:39]
	v_lshlrev_b32_e32 v44, 16, v27
	v_and_b32_e32 v45, 0xffff0000, v27
	v_add_f32_e32 v24, 1.0, v24
	v_rcp_f32_e32 v24, v24
	s_nop 0
	v_mul_f32_e32 v24, v36, v24
	v_mul_f32_e32 v36, 0xbfb8aa3b, v37
	v_exp_f32_e32 v36, v36
	v_mul_f32_e32 v24, v38, v24
	v_lshlrev_b32_e32 v38, 16, v35
	v_add_f32_e32 v36, 1.0, v36
	v_rcp_f32_e32 v36, v36
	s_nop 0
	v_mul_f32_e32 v36, v37, v36
	v_mul_f32_e32 v36, v39, v36
	v_cvt_pk_bf16_f32 v24, v24, v36
	v_and_b32_e32 v39, 0xffff0000, v35
	s_waitcnt lgkmcnt(0)
	v_pk_mul_f32 v[38:39], v[162:163], v[38:39] op_sel_hi:[0,1]
	v_pk_mul_f32 v[36:37], v[162:163], v[44:45] op_sel_hi:[0,1]
	v_pk_mul_f32 v[44:45], v[74:75], v[4:5]
	s_nop 0
	v_pk_fma_f32 v[42:43], v[70:71], v[42:43], v[44:45]
	v_pk_mul_f32 v[44:45], v[76:77], v[2:3]
	v_pk_fma_f32 v[42:43], v[78:79], v[38:39], v[42:43]
	v_pk_fma_f32 v[40:41], v[72:73], v[40:41], v[44:45]
	v_mul_f32_e32 v27, 0xbfb8aa3b, v42
	v_exp_f32_e32 v27, v27
	v_mul_f32_e32 v35, 0xbfb8aa3b, v43
	v_exp_f32_e32 v35, v35
	v_pk_fma_f32 v[40:41], v[80:81], v[36:37], v[40:41]
	v_add_f32_e32 v27, 1.0, v27
	v_rcp_f32_e32 v27, v27
	v_add_f32_e32 v35, 1.0, v35
	v_rcp_f32_e32 v35, v35
	v_mul_f32_e32 v27, v42, v27
	v_mul_f32_e32 v27, v40, v27
	v_mul_f32_e32 v35, v43, v35
	v_mul_f32_e32 v35, v41, v35
	v_lshlrev_b32_e32 v42, 16, v34
	v_and_b32_e32 v43, 0xffff0000, v34
	v_cvt_pk_bf16_f32 v27, v27, v35
	s_waitcnt lgkmcnt(0)
	v_pk_mul_f32 v[34:35], v[164:165], v[42:43] op_sel_hi:[0,1]
	v_lshlrev_b32_e32 v42, 16, v30
	v_and_b32_e32 v43, 0xffff0000, v30
	v_pk_mul_f32 v[40:41], v[164:165], v[42:43] op_sel_hi:[0,1]
	v_pk_mul_f32 v[42:43], v[74:75], v[38:39]
	s_nop 0
	v_pk_fma_f32 v[4:5], v[70:71], v[4:5], v[42:43]
	v_pk_mul_f32 v[42:43], v[76:77], v[36:37]
	v_pk_fma_f32 v[4:5], v[78:79], v[34:35], v[4:5]
	v_pk_fma_f32 v[2:3], v[72:73], v[2:3], v[42:43]
	v_mul_f32_e32 v30, 0xbfb8aa3b, v4
	v_exp_f32_e32 v30, v30
	v_pk_fma_f32 v[2:3], v[80:81], v[40:41], v[2:3]
	v_lshlrev_b32_e32 v42, 16, v32
	v_and_b32_e32 v43, 0xffff0000, v32
	v_add_f32_e32 v30, 1.0, v30
	v_rcp_f32_e32 v30, v30
	s_nop 0
	v_mul_f32_e32 v4, v4, v30
	v_mul_f32_e32 v2, v2, v4
	v_mul_f32_e32 v4, 0xbfb8aa3b, v5
	v_exp_f32_e32 v4, v4
	s_nop 0
	v_add_f32_e32 v4, 1.0, v4
	v_rcp_f32_e32 v4, v4
	s_nop 0
	v_mul_f32_e32 v4, v5, v4
	v_mul_f32_e32 v3, v3, v4
	v_cvt_pk_bf16_f32 v30, v2, v3
	v_lshlrev_b32_e32 v4, 16, v33
	v_and_b32_e32 v5, 0xffff0000, v33
	v_pk_mul_f32 v[32:33], v[74:75], v[34:35]
	s_waitcnt lgkmcnt(0)
	v_pk_mul_f32 v[4:5], v[166:167], v[4:5] op_sel_hi:[0,1]
	v_pk_fma_f32 v[32:33], v[70:71], v[38:39], v[32:33]
	v_pk_mul_f32 v[38:39], v[76:77], v[40:41]
	v_pk_fma_f32 v[32:33], v[78:79], v[4:5], v[32:33]
	v_pk_fma_f32 v[36:37], v[72:73], v[36:37], v[38:39]
	v_mul_f32_e32 v38, 0xbfb8aa3b, v32
	v_exp_f32_e32 v38, v38
	v_pk_mul_f32 v[2:3], v[166:167], v[42:43] op_sel_hi:[0,1]
	v_pk_fma_f32 v[36:37], v[80:81], v[2:3], v[36:37]
	v_and_b32_e32 v39, 0xffff0000, v31
	v_add_f32_e32 v38, 1.0, v38
	v_rcp_f32_e32 v38, v38
	v_lshlrev_b32_e32 v42, 16, v29
	v_and_b32_e32 v43, 0xffff0000, v29
	v_mul_f32_e32 v32, v32, v38
	v_mul_f32_e32 v32, v36, v32
	v_mul_f32_e32 v36, 0xbfb8aa3b, v33
	v_exp_f32_e32 v36, v36
	v_lshlrev_b32_e32 v38, 16, v31
	v_add_f32_e32 v36, 1.0, v36
	v_rcp_f32_e32 v36, v36
	s_nop 0
	v_mul_f32_e32 v33, v33, v36
	v_mul_f32_e32 v33, v37, v33
	v_cvt_pk_bf16_f32 v32, v32, v33
	s_waitcnt lgkmcnt(0)
	v_pk_mul_f32 v[38:39], v[168:169], v[38:39] op_sel_hi:[0,1]
	v_pk_mul_f32 v[36:37], v[168:169], v[42:43] op_sel_hi:[0,1]
	v_pk_mul_f32 v[42:43], v[74:75], v[4:5]
	s_nop 0
	v_pk_fma_f32 v[34:35], v[70:71], v[34:35], v[42:43]
	v_pk_mul_f32 v[42:43], v[76:77], v[2:3]
	v_pk_fma_f32 v[34:35], v[78:79], v[38:39], v[34:35]
	v_pk_fma_f32 v[40:41], v[72:73], v[40:41], v[42:43]
	v_mul_f32_e32 v29, 0xbfb8aa3b, v34
	v_exp_f32_e32 v29, v29
	v_mul_f32_e32 v31, 0xbfb8aa3b, v35
	v_exp_f32_e32 v31, v31
	v_pk_fma_f32 v[40:41], v[80:81], v[36:37], v[40:41]
	v_add_f32_e32 v29, 1.0, v29
	v_rcp_f32_e32 v29, v29
	v_add_f32_e32 v31, 1.0, v31
	v_rcp_f32_e32 v31, v31
	v_lshlrev_b32_e32 v42, 16, v26
	v_mul_f32_e32 v29, v34, v29
	v_mul_f32_e32 v31, v35, v31
	v_mul_f32_e32 v29, v40, v29
	v_mul_f32_e32 v31, v41, v31
	v_lshlrev_b32_e32 v40, 16, v28
	v_and_b32_e32 v41, 0xffff0000, v28
	v_and_b32_e32 v43, 0xffff0000, v26
	s_waitcnt lgkmcnt(0)
	v_pk_mul_f32 v[40:41], v[170:171], v[40:41] op_sel_hi:[0,1]
	v_pk_mul_f32 v[34:35], v[170:171], v[42:43] op_sel_hi:[0,1]
	v_pk_mul_f32 v[42:43], v[74:75], v[38:39]
	v_cvt_pk_bf16_f32 v29, v29, v31
	s_nop 0
	v_pk_fma_f32 v[4:5], v[70:71], v[4:5], v[42:43]
	v_pk_mul_f32 v[42:43], v[76:77], v[36:37]
	v_pk_fma_f32 v[4:5], v[78:79], v[40:41], v[4:5]
	v_pk_fma_f32 v[2:3], v[72:73], v[2:3], v[42:43]
	v_mul_f32_e32 v26, 0xbfb8aa3b, v4
	v_exp_f32_e32 v26, v26
	v_pk_fma_f32 v[2:3], v[80:81], v[34:35], v[2:3]
	v_add_f32_e32 v26, 1.0, v26
	v_rcp_f32_e32 v26, v26
	s_nop 0
	v_mul_f32_e32 v4, v4, v26
	v_mul_f32_e32 v2, v2, v4
	v_mul_f32_e32 v4, 0xbfb8aa3b, v5
	v_exp_f32_e32 v4, v4
	s_nop 0
	v_add_f32_e32 v4, 1.0, v4
	v_rcp_f32_e32 v4, v4
	s_nop 0
	v_mul_f32_e32 v4, v5, v4
	v_mul_f32_e32 v3, v3, v4
	v_cvt_pk_bf16_f32 v26, v2, v3
	v_lshlrev_b32_e32 v4, 16, v25
	v_and_b32_e32 v5, 0xffff0000, v25
	s_waitcnt lgkmcnt(0)
	v_pk_mul_f32 v[42:43], v[172:173], v[4:5] op_sel_hi:[0,1]
	v_lshlrev_b32_e32 v4, 16, v23
	v_and_b32_e32 v5, 0xffff0000, v23
	v_pk_mul_f32 v[44:45], v[172:173], v[4:5] op_sel_hi:[0,1]
	v_pk_mul_f32 v[2:3], v[74:75], v[40:41]
	v_pk_mul_f32 v[4:5], v[76:77], v[34:35]
	v_pk_fma_f32 v[2:3], v[70:71], v[38:39], v[2:3]
	v_pk_fma_f32 v[4:5], v[72:73], v[36:37], v[4:5]
	v_pk_fma_f32 v[2:3], v[78:79], v[42:43], v[2:3]
	v_pk_fma_f32 v[4:5], v[80:81], v[44:45], v[4:5]
	v_mul_f32_e32 v23, 0xbfb8aa3b, v2
	v_exp_f32_e32 v23, v23
	s_nop 0
	v_add_f32_e32 v23, 1.0, v23
	v_rcp_f32_e32 v23, v23
	s_nop 0
	v_mul_f32_e32 v2, v2, v23
	v_mul_f32_e32 v2, v4, v2
	v_mul_f32_e32 v4, 0xbfb8aa3b, v3
	v_exp_f32_e32 v4, v4
	s_nop 0
	v_add_f32_e32 v4, 1.0, v4
	v_rcp_f32_e32 v4, v4
	s_nop 0
	v_mul_f32_e32 v3, v3, v4
	v_mul_f32_e32 v3, v5, v3
	v_cvt_pk_bf16_f32 v23, v2, v3
	v_lshlrev_b32_e32 v4, 16, v22
	v_and_b32_e32 v5, 0xffff0000, v22
	s_waitcnt lgkmcnt(0)
	v_pk_mul_f32 v[36:37], v[174:175], v[4:5] op_sel_hi:[0,1]
	v_lshlrev_b32_e32 v4, 16, v21
	v_and_b32_e32 v5, 0xffff0000, v21
	v_pk_mul_f32 v[38:39], v[174:175], v[4:5] op_sel_hi:[0,1]
	v_pk_mul_f32 v[2:3], v[74:75], v[42:43]
	v_pk_mul_f32 v[4:5], v[76:77], v[44:45]
	v_pk_fma_f32 v[2:3], v[70:71], v[40:41], v[2:3]
	v_pk_fma_f32 v[4:5], v[72:73], v[34:35], v[4:5]
	v_pk_fma_f32 v[2:3], v[78:79], v[36:37], v[2:3]
	v_pk_fma_f32 v[4:5], v[80:81], v[38:39], v[4:5]
	v_mul_f32_e32 v21, 0xbfb8aa3b, v2
	v_exp_f32_e32 v21, v21
	v_lshlrev_b32_e32 v34, 16, v18
	v_and_b32_e32 v35, 0xffff0000, v18
	v_add_f32_e32 v21, 1.0, v21
	v_rcp_f32_e32 v21, v21
	s_nop 0
	v_mul_f32_e32 v2, v2, v21
	v_mul_f32_e32 v2, v4, v2
	v_mul_f32_e32 v4, 0xbfb8aa3b, v3
	v_exp_f32_e32 v4, v4
	s_nop 0
	v_add_f32_e32 v4, 1.0, v4
	v_rcp_f32_e32 v4, v4
	s_nop 0
	v_mul_f32_e32 v3, v3, v4
	v_mul_f32_e32 v3, v5, v3
	v_cvt_pk_bf16_f32 v21, v2, v3
	v_lshlrev_b32_e32 v2, 16, v19
	v_and_b32_e32 v3, 0xffff0000, v19
	v_pk_mul_f32 v[18:19], v[74:75], v[36:37]
	s_waitcnt lgkmcnt(0)
	v_pk_mul_f32 v[2:3], v[176:177], v[2:3] op_sel_hi:[0,1]
	v_pk_fma_f32 v[18:19], v[70:71], v[42:43], v[18:19]
	v_pk_mul_f32 v[4:5], v[176:177], v[34:35] op_sel_hi:[0,1]
	v_pk_fma_f32 v[18:19], v[78:79], v[2:3], v[18:19]
	v_pk_mul_f32 v[34:35], v[76:77], v[38:39]
	v_mul_f32_e32 v22, 0xbfb8aa3b, v18
	v_exp_f32_e32 v22, v22
	v_pk_fma_f32 v[34:35], v[72:73], v[44:45], v[34:35]
	v_add_f32_e32 v22, 1.0, v22
	v_rcp_f32_e32 v22, v22
	v_pk_fma_f32 v[34:35], v[80:81], v[4:5], v[34:35]
	v_mul_f32_e32 v18, v18, v22
	v_mul_f32_e32 v22, 0xbfb8aa3b, v19
	v_exp_f32_e32 v22, v22
	v_mul_f32_e32 v18, v34, v18
	v_lshlrev_b32_e32 v34, 16, v17
	v_add_f32_e32 v22, 1.0, v22
	v_rcp_f32_e32 v22, v22
	s_nop 0
	v_mul_f32_e32 v19, v19, v22
	v_mul_f32_e32 v19, v35, v19
	v_and_b32_e32 v35, 0xffff0000, v17
	v_cvt_pk_bf16_f32 v18, v18, v19
	s_waitcnt lgkmcnt(0)
	v_pk_mul_f32 v[82:83], v[178:179], v[34:35] op_sel_hi:[0,1]
	v_lshlrev_b32_e32 v34, 16, v16
	v_and_b32_e32 v35, 0xffff0000, v16
	v_pk_mul_f32 v[16:17], v[74:75], v[2:3]
	v_pk_mul_f32 v[84:85], v[178:179], v[34:35] op_sel_hi:[0,1]
	v_pk_fma_f32 v[16:17], v[70:71], v[36:37], v[16:17]
	v_pk_mul_f32 v[34:35], v[76:77], v[4:5]
	v_pk_fma_f32 v[16:17], v[78:79], v[82:83], v[16:17]
	v_pk_fma_f32 v[34:35], v[72:73], v[38:39], v[34:35]
	v_mul_f32_e32 v19, 0xbfb8aa3b, v16
	v_exp_f32_e32 v19, v19
	v_pk_fma_f32 v[34:35], v[80:81], v[84:85], v[34:35]
	v_add_f32_e32 v19, 1.0, v19
	v_rcp_f32_e32 v19, v19
	s_nop 0
	v_mul_f32_e32 v16, v16, v19
	v_mul_f32_e32 v19, 0xbfb8aa3b, v17
	v_exp_f32_e32 v19, v19
	v_mul_f32_e32 v16, v34, v16
	v_add_f32_e32 v19, 1.0, v19
	v_rcp_f32_e32 v19, v19
	s_nop 0
	v_mul_f32_e32 v17, v17, v19
	v_mul_f32_e32 v17, v35, v17
	v_cvt_pk_bf16_f32 v16, v16, v17
	v_cndmask_b32_e64 v17, 0, 1, s[16:17]
	v_cmp_ne_u32_e64 s[2:3], 1, v17
	s_cbranch_vccz .LBB0_221
	s_andn2_b64 vcc, exec, s[22:23]
	s_cbranch_vccz .LBB0_222

.LBB0_218:
	v_lshlrev_b32_e32 v34, 16, v13
	v_and_b32_e32 v35, 0xffff0000, v13
	s_add_i32 s24, s39, 15
	s_mov_b64 s[22:23], -1
	s_waitcnt lgkmcnt(0)
	v_pk_mul_f32 v[86:87], v[180:181], v[34:35] op_sel_hi:[0,1]
	v_lshlrev_b32_e32 v34, 16, v12
	v_and_b32_e32 v35, 0xffff0000, v12
	v_pk_mul_f32 v[12:13], v[74:75], v[82:83]
	v_pk_mul_f32 v[88:89], v[180:181], v[34:35] op_sel_hi:[0,1]
	v_pk_fma_f32 v[2:3], v[70:71], v[2:3], v[12:13]
	v_pk_mul_f32 v[12:13], v[76:77], v[84:85]
	v_pk_fma_f32 v[2:3], v[78:79], v[86:87], v[2:3]
	v_pk_fma_f32 v[4:5], v[72:73], v[4:5], v[12:13]
	v_mul_f32_e32 v12, 0xbfb8aa3b, v2
	v_exp_f32_e32 v12, v12
	v_pk_fma_f32 v[4:5], v[80:81], v[88:89], v[4:5]
	s_and_b64 vcc, exec, s[2:3]
	v_add_f32_e32 v12, 1.0, v12
	v_rcp_f32_e32 v12, v12
	s_nop 0
	v_mul_f32_e32 v2, v2, v12
	v_mul_f32_e32 v2, v4, v2
	v_mul_f32_e32 v4, 0xbfb8aa3b, v3
	v_exp_f32_e32 v4, v4
	s_nop 0
	v_add_f32_e32 v4, 1.0, v4
	v_rcp_f32_e32 v4, v4
	s_nop 0
	v_mul_f32_e32 v3, v3, v4
	v_mul_f32_e32 v3, v5, v3
	v_cvt_pk_bf16_f32 v2, v2, v3
	s_cbranch_vccz .LBB0_223
	s_andn2_b64 vcc, exec, s[22:23]
	s_cbranch_vccz .LBB0_224
